# hyena u-phase tiles: all 36 neighbour loads in flight
# speedup vs baseline: 1.0692x; 1.0056x over previous
; __device__ __forceinline__ float bf2f(bf16 b) { return __uint_as_float(((unsigned)b) << 16); }
; __device__ __forceinline__ void hy_u_tile(const Params& p, int layer, int item, float* sT) {
;     ...
;   {
;     const int cl = tid & 63, tq = tid >> 6;
;     const int c = c0 + cl;
;     const float wv0 = cw[c], wv1 = cw[1536 + c], wv2 = cw[3072 + c], bv = cb[c];
;     const float wx0 = cw[512 + c], wx1 = cw[1536 + 512 + c], wx2 = cw[3072 + 512 + c], bx = cb[512 + c];
;     const int ts = t0 + tq * 16;
;     const int L = tok_len(ts);
;     int pos = tok_pos(ts);
;     const int tpv = pos > 0 ? ts - 1 : ts;
;     float vp = bf2f(p.hv[(size_t)tpv * 512 + c]);
;     float xp = bf2f(p.hx1[(size_t)tpv * 512 + c]);
;     vp = pos > 0 ? vp : 0.f;
;     xp = pos > 0 ? xp : 0.f;
;     float vc = bf2f(p.hv[(size_t)ts * 512 + c]);
;     float xc = bf2f(p.hx1[(size_t)ts * 512 + c]);
; #pragma unroll
;     for (int j = 0; j < 16; ++j) {
;       const int t = ts + j;
;       const bool hn = (pos + j) < L - 1;
;       const int tn = hn ? t + 1 : t;
;       float vn = bf2f(p.hv[(size_t)tn * 512 + c]);
;       float xn = bf2f(p.hx1[(size_t)tn * 512 + c]);
;       vn = hn ? vn : 0.f;
;       xn = hn ? xn : 0.f;
.LBB0_1560:
	s_or_b64 exec, exec, s[24:25]
	s_waitcnt lgkmcnt(0)
	s_barrier
	ds_read_b32 v0, v220
	s_movk_i32 s0, 0x13ff
	s_mov_b64 s[24:25], -1
	s_waitcnt lgkmcnt(0)
	v_cmp_lt_i32_e32 vcc, s0, v0
	v_readfirstlane_b32 s36, v0
	s_cbranch_vccnz .LBB0_1555
	s_cmpk_gt_i32 s36, 0x3ff
	s_cbranch_scc0 .LBB0_1563
	s_add_i32 s24, s36, 0xfffffc00
	s_lshl_b32 s0, s24, 3
	s_lshl_b32 s24, s24, 6
	v_mov_b32_e32 v5, v195
	s_and_b32 s24, s24, 0x1c0
	s_and_b32 s0, s0, 0x7fc0
	v_and_b32_e32 v9, 63, v5
	v_or_b32_e32 v13, s24, v9
	v_lshlrev_b32_e32 v0, 2, v13
	v_lshl_add_u64 v[10:11], s[20:21], 0, v[0:1]
	v_add_co_u32_e32 v6, vcc, 0x1000, v10
	global_load_dword v3, v0, s[20:21]
	s_nop 0
	v_addc_co_u32_e32 v7, vcc, 0, v11, vcc
	global_load_dword v2, v[6:7], off offset:2048
	v_add_co_u32_e32 v14, vcc, 0x3000, v10
	v_ashrrev_i32_e32 v7, 2, v5
	s_nop 0
	v_addc_co_u32_e32 v15, vcc, 0, v11, vcc
	v_and_b32_e32 v20, -16, v7
	v_add_co_u32_e32 v10, vcc, 0x2000, v10
	v_add_u32_e32 v16, s0, v20
	s_nop 0
	v_addc_co_u32_e32 v11, vcc, 0, v11, vcc
	v_ashrrev_i32_e32 v17, 31, v16
	global_load_dword v4, v[14:15], off
	global_load_dword v8, v0, s[22:23]
	global_load_dword v6, v0, s[20:21] offset:2048
	global_load_dword v12, v[10:11], off
	s_nop 0
	global_load_dword v10, v[14:15], off offset:2048
	s_nop 0
	global_load_dword v0, v0, s[22:23] offset:2048
	v_readlane_b32 s74, v252, 33
	v_readlane_b32 s75, v252, 34
	v_readlane_b32 s76, v252, 35
	v_readlane_b32 s77, v252, 36
	s_lshl_b32 s0, s0, 1
	s_movk_i32 s25, 0x104
	v_lshlrev_b32_e32 v11, 1, v13
	v_mov_b32_e32 v30, v11
	v_mov_b32_e32 v31, 0
	v_lshl_add_u64 v[32:33], s[74:75], 0, v[30:31]
	v_lshl_add_u64 v[38:39], s[76:77], 0, v[30:31]
	s_movk_i32 s28, 0x4000
	v_cmp_gt_i32_e32 vcc, s28, v16
	v_and_b32_e32 v22, 0x7f0, v16
	v_lshlrev_b32_e32 v14, 2, v20
	v_mad_u32_u24 v9, v9, s25, v14
	v_cndmask_b32_e32 v15, v22, v16, vcc
	v_cndmask_b32_e32 v13, v225, v226, vcc
	v_cmp_lt_i32_e64 s[40:41], 0, v15
	v_add_u32_e32 v14, 15, v15
	v_cmp_lt_i32_e32 vcc, v14, v13
	v_subbrev_co_u32_e64 v22, s[42:43], 0, v16, s[40:41]
	v_ashrrev_i32_e32 v23, 31, v22
	v_lshlrev_b64 v[22:23], 10, v[22:23]
	v_lshl_add_u64 v[24:25], v[32:33], 0, v[22:23]
	global_load_ushort v40, v[24:25], off
	v_lshl_add_u64 v[24:25], v[38:39], 0, v[22:23]
	global_load_ushort v60, v[24:25], off
	v_mov_b32_e32 v22, v16
	v_ashrrev_i32_e32 v23, 31, v22
	v_lshlrev_b64 v[22:23], 10, v[22:23]
	v_lshl_add_u64 v[24:25], v[32:33], 0, v[22:23]
	global_load_ushort v41, v[24:25], off
	v_lshl_add_u64 v[24:25], v[38:39], 0, v[22:23]
	global_load_ushort v61, v[24:25], off
	v_add_u32_e32 v22, 1, v16
	v_ashrrev_i32_e32 v23, 31, v22
	v_lshlrev_b64 v[22:23], 10, v[22:23]
	v_lshl_add_u64 v[24:25], v[32:33], 0, v[22:23]
	global_load_ushort v42, v[24:25], off
	v_lshl_add_u64 v[24:25], v[38:39], 0, v[22:23]
	global_load_ushort v62, v[24:25], off
	v_add_u32_e32 v22, 2, v16
	v_ashrrev_i32_e32 v23, 31, v22
	v_lshlrev_b64 v[22:23], 10, v[22:23]
	v_lshl_add_u64 v[24:25], v[32:33], 0, v[22:23]
	global_load_ushort v43, v[24:25], off
	v_lshl_add_u64 v[24:25], v[38:39], 0, v[22:23]
	global_load_ushort v63, v[24:25], off
	v_add_u32_e32 v22, 3, v16
	v_ashrrev_i32_e32 v23, 31, v22
	v_lshlrev_b64 v[22:23], 10, v[22:23]
	v_lshl_add_u64 v[24:25], v[32:33], 0, v[22:23]
	global_load_ushort v44, v[24:25], off
	v_lshl_add_u64 v[24:25], v[38:39], 0, v[22:23]
	global_load_ushort v64, v[24:25], off
	v_add_u32_e32 v22, 4, v16
	v_ashrrev_i32_e32 v23, 31, v22
	v_lshlrev_b64 v[22:23], 10, v[22:23]
	v_lshl_add_u64 v[24:25], v[32:33], 0, v[22:23]
	global_load_ushort v45, v[24:25], off
	v_lshl_add_u64 v[24:25], v[38:39], 0, v[22:23]
	global_load_ushort v65, v[24:25], off
	v_add_u32_e32 v22, 5, v16
	v_ashrrev_i32_e32 v23, 31, v22
	v_lshlrev_b64 v[22:23], 10, v[22:23]
	v_lshl_add_u64 v[24:25], v[32:33], 0, v[22:23]
	global_load_ushort v46, v[24:25], off
	v_lshl_add_u64 v[24:25], v[38:39], 0, v[22:23]
	global_load_ushort v66, v[24:25], off
	v_add_u32_e32 v22, 6, v16
	v_ashrrev_i32_e32 v23, 31, v22
	v_lshlrev_b64 v[22:23], 10, v[22:23]
	v_lshl_add_u64 v[24:25], v[32:33], 0, v[22:23]
	global_load_ushort v47, v[24:25], off
	v_lshl_add_u64 v[24:25], v[38:39], 0, v[22:23]
	global_load_ushort v67, v[24:25], off
	v_add_u32_e32 v22, 7, v16
	v_ashrrev_i32_e32 v23, 31, v22
	v_lshlrev_b64 v[22:23], 10, v[22:23]
	v_lshl_add_u64 v[24:25], v[32:33], 0, v[22:23]
	global_load_ushort v48, v[24:25], off
	v_lshl_add_u64 v[24:25], v[38:39], 0, v[22:23]
	global_load_ushort v68, v[24:25], off
	v_add_u32_e32 v22, 8, v16
	v_ashrrev_i32_e32 v23, 31, v22
	v_lshlrev_b64 v[22:23], 10, v[22:23]
	v_lshl_add_u64 v[24:25], v[32:33], 0, v[22:23]
	global_load_ushort v49, v[24:25], off
	v_lshl_add_u64 v[24:25], v[38:39], 0, v[22:23]
	global_load_ushort v69, v[24:25], off
	v_add_u32_e32 v22, 9, v16
	v_ashrrev_i32_e32 v23, 31, v22
	v_lshlrev_b64 v[22:23], 10, v[22:23]
	v_lshl_add_u64 v[24:25], v[32:33], 0, v[22:23]
	global_load_ushort v50, v[24:25], off
	v_lshl_add_u64 v[24:25], v[38:39], 0, v[22:23]
	global_load_ushort v70, v[24:25], off
	v_add_u32_e32 v22, 10, v16
	v_ashrrev_i32_e32 v23, 31, v22
	v_lshlrev_b64 v[22:23], 10, v[22:23]
	v_lshl_add_u64 v[24:25], v[32:33], 0, v[22:23]
	global_load_ushort v51, v[24:25], off
	v_lshl_add_u64 v[24:25], v[38:39], 0, v[22:23]
	global_load_ushort v71, v[24:25], off
	v_add_u32_e32 v22, 11, v16
	v_ashrrev_i32_e32 v23, 31, v22
	v_lshlrev_b64 v[22:23], 10, v[22:23]
	v_lshl_add_u64 v[24:25], v[32:33], 0, v[22:23]
	global_load_ushort v52, v[24:25], off
	v_lshl_add_u64 v[24:25], v[38:39], 0, v[22:23]
	global_load_ushort v72, v[24:25], off
	v_add_u32_e32 v22, 12, v16
	v_ashrrev_i32_e32 v23, 31, v22
	v_lshlrev_b64 v[22:23], 10, v[22:23]
	v_lshl_add_u64 v[24:25], v[32:33], 0, v[22:23]
	global_load_ushort v53, v[24:25], off
	v_lshl_add_u64 v[24:25], v[38:39], 0, v[22:23]
	global_load_ushort v73, v[24:25], off
	v_add_u32_e32 v22, 13, v16
	v_ashrrev_i32_e32 v23, 31, v22
	v_lshlrev_b64 v[22:23], 10, v[22:23]
	v_lshl_add_u64 v[24:25], v[32:33], 0, v[22:23]
	global_load_ushort v54, v[24:25], off
	v_lshl_add_u64 v[24:25], v[38:39], 0, v[22:23]
	global_load_ushort v74, v[24:25], off
	v_add_u32_e32 v22, 14, v16
	v_ashrrev_i32_e32 v23, 31, v22
	v_lshlrev_b64 v[22:23], 10, v[22:23]
	v_lshl_add_u64 v[24:25], v[32:33], 0, v[22:23]
	global_load_ushort v55, v[24:25], off
	v_lshl_add_u64 v[24:25], v[38:39], 0, v[22:23]
	global_load_ushort v75, v[24:25], off
	v_add_u32_e32 v22, 15, v16
	v_ashrrev_i32_e32 v23, 31, v22
	v_lshlrev_b64 v[22:23], 10, v[22:23]
	v_lshl_add_u64 v[24:25], v[32:33], 0, v[22:23]
	global_load_ushort v56, v[24:25], off
	v_lshl_add_u64 v[24:25], v[38:39], 0, v[22:23]
	global_load_ushort v76, v[24:25], off
	v_addc_co_u32_e64 v22, s[42:43], 15, v16, vcc
	v_ashrrev_i32_e32 v23, 31, v22
	v_lshlrev_b64 v[22:23], 10, v[22:23]
	v_lshl_add_u64 v[24:25], v[32:33], 0, v[22:23]
	global_load_ushort v57, v[24:25], off
	v_lshl_add_u64 v[24:25], v[38:39], 0, v[22:23]
	global_load_ushort v77, v[24:25], off
	s_waitcnt vmcnt(0)
; __device__ __forceinline__ float bf2f(bf16 b) { return __uint_as_float(((unsigned)b) << 16); }
; __device__ __forceinline__ void hy_u_tile(const Params& p, int layer, int item, float* sT) {
;     ...
; #pragma unroll
;     for (int j = 0; j < 16; ++j) {
;       const int t = ts + j;
;       const bool hn = (pos + j) < L - 1;
;       const int tn = hn ? t + 1 : t;
;       float vn = bf2f(p.hv[(size_t)tn * 512 + c]);
;       float xn = bf2f(p.hx1[(size_t)tn * 512 + c]);
;       vn = hn ? vn : 0.f;
;       xn = hn ? xn : 0.f;
;       float a = vp * wv0 + vc * wv1 + vn * wv2 + bv;
;       float b = xp * wx0 + xc * wx1 + xn * wx2 + bx;
;       sT[cl * 65 + tq * 16 + j] = a * b;
;       vp = vc; vc = vn; xp = xc; xc = xn;
;     }
;   }
;   __syncthreads();
	v_lshlrev_b32_e32 v40, 16, v40
	v_lshlrev_b32_e32 v60, 16, v60
	v_lshlrev_b32_e32 v41, 16, v41
	v_lshlrev_b32_e32 v61, 16, v61
	v_lshlrev_b32_e32 v42, 16, v42
	v_lshlrev_b32_e32 v62, 16, v62
	v_lshlrev_b32_e32 v43, 16, v43
	v_lshlrev_b32_e32 v63, 16, v63
	v_lshlrev_b32_e32 v44, 16, v44
	v_lshlrev_b32_e32 v64, 16, v64
	v_lshlrev_b32_e32 v45, 16, v45
	v_lshlrev_b32_e32 v65, 16, v65
	v_lshlrev_b32_e32 v46, 16, v46
	v_lshlrev_b32_e32 v66, 16, v66
	v_lshlrev_b32_e32 v47, 16, v47
	v_lshlrev_b32_e32 v67, 16, v67
	v_lshlrev_b32_e32 v48, 16, v48
	v_lshlrev_b32_e32 v68, 16, v68
	v_lshlrev_b32_e32 v49, 16, v49
	v_lshlrev_b32_e32 v69, 16, v69
	v_lshlrev_b32_e32 v50, 16, v50
	v_lshlrev_b32_e32 v70, 16, v70
	v_lshlrev_b32_e32 v51, 16, v51
	v_lshlrev_b32_e32 v71, 16, v71
	v_lshlrev_b32_e32 v52, 16, v52
	v_lshlrev_b32_e32 v72, 16, v72
	v_lshlrev_b32_e32 v53, 16, v53
	v_lshlrev_b32_e32 v73, 16, v73
	v_lshlrev_b32_e32 v54, 16, v54
	v_lshlrev_b32_e32 v74, 16, v74
	v_lshlrev_b32_e32 v55, 16, v55
	v_lshlrev_b32_e32 v75, 16, v75
	v_lshlrev_b32_e32 v56, 16, v56
	v_lshlrev_b32_e32 v76, 16, v76
	v_lshlrev_b32_e32 v57, 16, v57
	v_lshlrev_b32_e32 v77, 16, v77
	v_cndmask_b32_e64 v40, 0, v40, s[40:41]
	v_cndmask_b32_e64 v60, 0, v60, s[40:41]
	v_cndmask_b32_e32 v57, 0, v57, vcc
	v_cndmask_b32_e32 v77, 0, v77, vcc
	v_mul_f32_e32 v26, v3, v40
	v_mul_f32_e32 v27, v6, v60
	v_fmac_f32_e32 v26, v2, v41
	v_fmac_f32_e32 v27, v12, v61
	v_fmac_f32_e32 v26, v4, v42
	v_fmac_f32_e32 v27, v10, v62
	v_add_f32_e32 v26, v8, v26
	v_add_f32_e32 v27, v0, v27
	v_mul_f32_e32 v26, v26, v27
	ds_write_b32 v9, v26
	v_mul_f32_e32 v26, v3, v41
	v_mul_f32_e32 v27, v6, v61
	v_fmac_f32_e32 v26, v2, v42
	v_fmac_f32_e32 v27, v12, v62
	v_fmac_f32_e32 v26, v4, v43
	v_fmac_f32_e32 v27, v10, v63
	v_add_f32_e32 v26, v8, v26
	v_add_f32_e32 v27, v0, v27
	v_mul_f32_e32 v26, v26, v27
	ds_write_b32 v9, v26 offset:4
	v_mul_f32_e32 v26, v3, v42
	v_mul_f32_e32 v27, v6, v62
	v_fmac_f32_e32 v26, v2, v43
	v_fmac_f32_e32 v27, v12, v63
	v_fmac_f32_e32 v26, v4, v44
	v_fmac_f32_e32 v27, v10, v64
	v_add_f32_e32 v26, v8, v26
	v_add_f32_e32 v27, v0, v27
	v_mul_f32_e32 v26, v26, v27
	ds_write_b32 v9, v26 offset:8
	v_mul_f32_e32 v26, v3, v43
	v_mul_f32_e32 v27, v6, v63
	v_fmac_f32_e32 v26, v2, v44
	v_fmac_f32_e32 v27, v12, v64
	v_fmac_f32_e32 v26, v4, v45
	v_fmac_f32_e32 v27, v10, v65
	v_add_f32_e32 v26, v8, v26
	v_add_f32_e32 v27, v0, v27
	v_mul_f32_e32 v26, v26, v27
	ds_write_b32 v9, v26 offset:12
	v_mul_f32_e32 v26, v3, v44
	v_mul_f32_e32 v27, v6, v64
	v_fmac_f32_e32 v26, v2, v45
	v_fmac_f32_e32 v27, v12, v65
	v_fmac_f32_e32 v26, v4, v46
	v_fmac_f32_e32 v27, v10, v66
	v_add_f32_e32 v26, v8, v26
	v_add_f32_e32 v27, v0, v27
	v_mul_f32_e32 v26, v26, v27
	ds_write_b32 v9, v26 offset:16
	v_mul_f32_e32 v26, v3, v45
	v_mul_f32_e32 v27, v6, v65
	v_fmac_f32_e32 v26, v2, v46
	v_fmac_f32_e32 v27, v12, v66
	v_fmac_f32_e32 v26, v4, v47
	v_fmac_f32_e32 v27, v10, v67
	v_add_f32_e32 v26, v8, v26
	v_add_f32_e32 v27, v0, v27
	v_mul_f32_e32 v26, v26, v27
	ds_write_b32 v9, v26 offset:20
	v_mul_f32_e32 v26, v3, v46
	v_mul_f32_e32 v27, v6, v66
	v_fmac_f32_e32 v26, v2, v47
	v_fmac_f32_e32 v27, v12, v67
	v_fmac_f32_e32 v26, v4, v48
	v_fmac_f32_e32 v27, v10, v68
	v_add_f32_e32 v26, v8, v26
	v_add_f32_e32 v27, v0, v27
	v_mul_f32_e32 v26, v26, v27
	ds_write_b32 v9, v26 offset:24
	v_mul_f32_e32 v26, v3, v47
	v_mul_f32_e32 v27, v6, v67
	v_fmac_f32_e32 v26, v2, v48
	v_fmac_f32_e32 v27, v12, v68
	v_fmac_f32_e32 v26, v4, v49
	v_fmac_f32_e32 v27, v10, v69
	v_add_f32_e32 v26, v8, v26
	v_add_f32_e32 v27, v0, v27
	v_mul_f32_e32 v26, v26, v27
	ds_write_b32 v9, v26 offset:28
	v_mul_f32_e32 v26, v3, v48
	v_mul_f32_e32 v27, v6, v68
	v_fmac_f32_e32 v26, v2, v49
	v_fmac_f32_e32 v27, v12, v69
	v_fmac_f32_e32 v26, v4, v50
	v_fmac_f32_e32 v27, v10, v70
	v_add_f32_e32 v26, v8, v26
	v_add_f32_e32 v27, v0, v27
	v_mul_f32_e32 v26, v26, v27
	ds_write_b32 v9, v26 offset:32
	v_mul_f32_e32 v26, v3, v49
	v_mul_f32_e32 v27, v6, v69
	v_fmac_f32_e32 v26, v2, v50
	v_fmac_f32_e32 v27, v12, v70
	v_fmac_f32_e32 v26, v4, v51
	v_fmac_f32_e32 v27, v10, v71
	v_add_f32_e32 v26, v8, v26
	v_add_f32_e32 v27, v0, v27
	v_mul_f32_e32 v26, v26, v27
	ds_write_b32 v9, v26 offset:36
	v_mul_f32_e32 v26, v3, v50
	v_mul_f32_e32 v27, v6, v70
	v_fmac_f32_e32 v26, v2, v51
	v_fmac_f32_e32 v27, v12, v71
	v_fmac_f32_e32 v26, v4, v52
	v_fmac_f32_e32 v27, v10, v72
	v_add_f32_e32 v26, v8, v26
	v_add_f32_e32 v27, v0, v27
	v_mul_f32_e32 v26, v26, v27
	ds_write_b32 v9, v26 offset:40
	v_mul_f32_e32 v26, v3, v51
	v_mul_f32_e32 v27, v6, v71
	v_fmac_f32_e32 v26, v2, v52
	v_fmac_f32_e32 v27, v12, v72
	v_fmac_f32_e32 v26, v4, v53
	v_fmac_f32_e32 v27, v10, v73
	v_add_f32_e32 v26, v8, v26
	v_add_f32_e32 v27, v0, v27
	v_mul_f32_e32 v26, v26, v27
	ds_write_b32 v9, v26 offset:44
	v_mul_f32_e32 v26, v3, v52
	v_mul_f32_e32 v27, v6, v72
	v_fmac_f32_e32 v26, v2, v53
	v_fmac_f32_e32 v27, v12, v73
	v_fmac_f32_e32 v26, v4, v54
	v_fmac_f32_e32 v27, v10, v74
	v_add_f32_e32 v26, v8, v26
	v_add_f32_e32 v27, v0, v27
	v_mul_f32_e32 v26, v26, v27
	ds_write_b32 v9, v26 offset:48
	v_mul_f32_e32 v26, v3, v53
	v_mul_f32_e32 v27, v6, v73
	v_fmac_f32_e32 v26, v2, v54
	v_fmac_f32_e32 v27, v12, v74
	v_fmac_f32_e32 v26, v4, v55
	v_fmac_f32_e32 v27, v10, v75
	v_add_f32_e32 v26, v8, v26
	v_add_f32_e32 v27, v0, v27
	v_mul_f32_e32 v26, v26, v27
	ds_write_b32 v9, v26 offset:52
	v_mul_f32_e32 v26, v3, v54
	v_mul_f32_e32 v27, v6, v74
	v_fmac_f32_e32 v26, v2, v55
	v_fmac_f32_e32 v27, v12, v75
	v_fmac_f32_e32 v26, v4, v56
	v_fmac_f32_e32 v27, v10, v76
	v_add_f32_e32 v26, v8, v26
	v_add_f32_e32 v27, v0, v27
	v_mul_f32_e32 v26, v26, v27
	ds_write_b32 v9, v26 offset:56
	v_mul_f32_e32 v26, v3, v55
	v_mul_f32_e32 v27, v6, v75
	v_fmac_f32_e32 v26, v2, v56
	v_fmac_f32_e32 v27, v12, v76
	v_fmac_f32_e32 v26, v4, v57
	v_fmac_f32_e32 v27, v10, v77
	v_add_f32_e32 v26, v8, v26
	v_add_f32_e32 v27, v0, v27
	v_mul_f32_e32 v26, v26, v27
	ds_write_b32 v9, v26 offset:60
	v_readlane_b32 s64, v254, 18
	v_readlane_b32 s65, v254, 19
	v_readlane_b32 s66, v254, 20
	v_readlane_b32 s67, v254, 21
	v_readlane_b32 s68, v254, 22
	v_readlane_b32 s69, v254, 23
	v_readlane_b32 s70, v254, 24
	v_readlane_b32 s71, v254, 25
	v_readlane_b32 s72, v254, 26
	v_readlane_b32 s73, v254, 27
	v_readlane_b32 s74, v254, 28
	v_readlane_b32 s75, v254, 29
	v_readlane_b32 s76, v254, 30
	v_readlane_b32 s77, v254, 31
	v_readlane_b32 s78, v254, 32
	v_readlane_b32 s79, v254, 33
	v_and_b32_e32 v0, 3, v5
	v_mul_lo_u32 v2, v7, s25
	v_lshl_add_u32 v6, v0, 6, v2
	s_waitcnt lgkmcnt(0)
	s_barrier
; __device__ __forceinline__ unsigned pack2(float a, float b) { f2_t f = {a, b}; return __builtin_bit_cast(unsigned, __builtin_convertvector(f, bf2_t)); }
; __device__ __forceinline__ void hy_u_tile(const Params& p, int layer, int item, float* sT) {
;     ...
;   {
;     const int cl = tid >> 2, sg = tid & 3;
;     unsigned u[8];
; #pragma unroll
;     for (int e = 0; e < 8; ++e) u[e] = pack2(sT[cl * 65 + sg * 16 + 2 * e], sT[cl * 65 + sg * 16 + 2 * e + 1]);
;     u4v* d4 = (u4v*)(p.uT + (size_t)(c0 + cl) * T_TOK + t0 + sg * 16);
;     d4[0] = (u4v){u[0], u[1], u[2], u[3]};
;     d4[1] = (u4v){u[4], u[5], u[6], u[7]};
;   }
;   __syncthreads();
	ds_read2_b32 v[2:3], v6 offset1:1
	ds_read2_b32 v[4:5], v6 offset0:2 offset1:3
	ds_read2_b32 v[8:9], v6 offset0:6 offset1:7
	ds_read2_b32 v[12:13], v6 offset0:14 offset1:15
	ds_read2_b32 v[10:11], v6 offset0:10 offset1:11
	s_waitcnt lgkmcnt(4)
	v_cvt_pk_bf16_f32 v2, v2, v3
	s_waitcnt lgkmcnt(3)
	v_cvt_pk_bf16_f32 v3, v4, v5
	ds_read2_b32 v[4:5], v6 offset0:4 offset1:5
	v_lshlrev_b32_e32 v0, 5, v0
	s_waitcnt lgkmcnt(0)
	v_cvt_pk_bf16_f32 v4, v4, v5
	v_cvt_pk_bf16_f32 v5, v8, v9
	ds_read2_b32 v[8:9], v6 offset0:8 offset1:9
	s_waitcnt lgkmcnt(0)
	v_cvt_pk_bf16_f32 v8, v8, v9
	v_cvt_pk_bf16_f32 v9, v10, v11
	ds_read2_b32 v[10:11], v6 offset0:12 offset1:13
	v_add_u32_e32 v6, s24, v7
	v_ashrrev_i32_e32 v7, 31, v6
	v_lshlrev_b64 v[6:7], 16, v[6:7]
	v_lshl_add_u64 v[6:7], s[74:75], 0, v[6:7]
	v_lshl_add_u64 v[6:7], v[6:7], 0, s[0:1]
	v_lshl_add_u64 v[6:7], v[6:7], 0, v[0:1]
	s_waitcnt lgkmcnt(0)
	v_cvt_pk_bf16_f32 v10, v10, v11
	v_cvt_pk_bf16_f32 v11, v12, v13
	global_store_dwordx4 v[6:7], v[2:5], off
	global_store_dwordx4 v[6:7], v[8:11], off offset:16
	s_barrier
	s_mov_b64 s[24:25], 0
